# recur phase: static placement of the 320 long chain items so that blocks b and b+256 (same CU) never both run heavy chains; dynamic queue for decode items
# speedup vs baseline: 1.0244x; 1.0092x over previous
.LBB0_285:
	s_or_b64 exec, exec, s[0:1]
	v_readlane_b32 s4, v254, 3
	v_readlane_b32 s18, v254, 17
	v_readlane_b32 s19, v254, 18
	s_add_u32 s0, s18, 0x5790000
	v_readlane_b32 s5, v254, 4
	v_readlane_b32 s6, v254, 5
	v_readlane_b32 s7, v254, 6
	v_readlane_b32 s8, v254, 7
	v_readlane_b32 s9, v254, 8
	v_readlane_b32 s10, v254, 9
	v_readlane_b32 s11, v254, 10
	v_readlane_b32 s12, v254, 11
	v_readlane_b32 s13, v254, 12
	v_readlane_b32 s14, v254, 13
	v_readlane_b32 s15, v254, 14
	v_readlane_b32 s16, v254, 15
	v_readlane_b32 s17, v254, 16
	v_writelane_b32 v254, s0, 62
	s_addc_u32 s0, s19, 0
	s_add_u32 s26, s74, 0x1000
	s_addc_u32 s27, s75, 0
	v_writelane_b32 v254, s0, 63
	s_add_u32 s0, s74, 0x1200
	s_addc_u32 s1, s75, 0
	s_mov_b32 s87, 0
	v_writelane_b32 v255, s0, 0
	v_mov_b32_e32 v28, 0
	s_movk_i32 s7, 0x1e20
	v_writelane_b32 v255, s1, 1
	s_add_u32 s0, s74, 0x1400
	s_addc_u32 s1, s75, 0
	v_writelane_b32 v255, s0, 2
	s_movk_i32 s24, 0x1000
	s_mov_b32 s90, 0xbfb8aa3b
	v_writelane_b32 v255, s1, 3
	s_add_u32 s0, s74, 0x1600
	s_addc_u32 s1, s75, 0
	v_writelane_b32 v255, s0, 4
	s_mov_b32 s91, 0x800000
	s_mov_b32 s92, 0x3f317217
	v_writelane_b32 v255, s1, 5
	s_add_u32 s0, s74, 0x1800
	s_addc_u32 s1, s75, 0
	v_writelane_b32 v255, s0, 6
	s_mov_b32 s93, 0x7f800000
	s_mov_b32 s6, 0x3e3504f3
	v_writelane_b32 v255, s1, 7
	s_add_u32 s0, s74, 0x1a00
	s_addc_u32 s1, s75, 0
	v_writelane_b32 v255, s0, 8
	s_movk_i32 s94, 0x800
	v_mov_b32_e32 v71, 0x42800000
	v_writelane_b32 v255, s1, 9
	s_add_u32 s0, s74, 0x1c00
	s_addc_u32 s1, s75, 0
	v_writelane_b32 v255, s0, 10
	v_mov_b32_e32 v72, 0x1800
	v_mov_b32_e32 v73, 0x1600
	v_writelane_b32 v255, s1, 11
	s_add_u32 s0, s74, 0x1e00
	s_addc_u32 s1, s75, 0
	v_writelane_b32 v255, s0, 12
	v_mov_b32_e32 v74, 0x3e000000
	v_mov_b32_e32 v75, 0x41b17218
	v_writelane_b32 v255, s1, 13
	s_add_u32 s0, s18, 0x4790000
	v_writelane_b32 v255, s0, 14
	s_addc_u32 s0, s19, 0
	v_writelane_b32 v255, s0, 15
	s_add_u32 s0, s18, 0x7090000
	v_writelane_b32 v255, s0, 16
	s_addc_u32 s0, s19, 0
	v_writelane_b32 v255, s0, 17
	s_add_u32 s0, s18, 0x5f90000
	v_writelane_b32 v255, s0, 18
	s_addc_u32 s0, s19, 0
	s_add_u32 s31, s18, 0x4690000
	v_writelane_b32 v255, s0, 19
	s_addc_u32 s0, s19, 0
	v_writelane_b32 v255, s0, 20
	s_add_u32 s0, s18, 0x4500000
	v_writelane_b32 v255, s0, 22
	s_addc_u32 s0, s19, 0
	v_writelane_b32 v255, s0, 24
	s_add_u32 s0, s18, 0x4400000
	v_writelane_b32 v255, s0, 26
	s_addc_u32 s0, s19, 0
	v_writelane_b32 v255, s0, 42
	s_add_i32 s3, 0, 0x10010
	s_add_i32 s0, 0, 0x3000
	v_writelane_b32 v255, s0, 44
	v_mov_b32_e32 v70, s3
	v_mov_b32_e32 v76, 0xc00
	v_mov_b32_e32 v77, 0xb00
	v_mov_b32_e32 v78, 0x1000
	s_waitcnt lgkmcnt(0)
	s_barrier
	s_mov_b32 s99, -1
	s_mov_b32 s100, 0
	s_cmp_lg_u32 s28, 0x200
	s_cbranch_scc1 .Lmap_done_0
	s_movk_i32 s100, 0x140
	s_cmp_ge_u32 s2, 0x100
	s_cbranch_scc1 .Lmap_hi_0
	s_mov_b32 s99, s2
	s_cmp_lt_u32 s2, 160
	s_cbranch_scc1 .Lmap_done_0
	s_add_u32 s99, s2, 0x60
	s_cmp_lt_u32 s2, 192
	s_cbranch_scc1 .Lmap_done_0
	s_sub_u32 s99, s2, 32
	s_cmp_lt_u32 s2, 224
	s_cbranch_scc1 .Lmap_done_0
	s_add_u32 s99, s2, 64
	s_branch .Lmap_done_0
.Lmap_hi_0:
	s_cmp_lt_u32 s2, 384
	s_cbranch_scc1 .Lmap_done_0
	s_cmp_ge_u32 s2, 448
	s_cbranch_scc1 .Lmap_done_0
	s_sub_u32 s99, s2, 192

.LBB0_289:
	v_mov_b32_e32 v0, v174
	s_nop 0
	v_cmp_eq_u32_e32 vcc, 0, v0
	s_and_saveexec_b64 s[0:1], vcc
	s_cbranch_execz .LBB0_293
	s_cmp_eq_u32 s99, -1
	s_cbranch_scc1 .Lq_dyn_0
	v_mov_b32_e32 v0, s99
	s_mov_b32 s99, -1
	s_waitcnt vmcnt(0)
	s_branch .Lq_wr_0
.Lq_dyn_0:
	v_mov_b32_e32 v1, 1
	global_atomic_add v1, v28, v1, s[48:49] sc0
	s_waitcnt vmcnt(0)
	v_add_u32_e32 v0, s100, v1
.Lq_wr_0:
	v_mov_b32_e32 v1, s3
	s_nop 0
	ds_write_b32 v1, v0

.LBB0_1268:
	s_or_b64 exec, exec, s[0:1]
	v_readlane_b32 s52, v255, 26
	v_readlane_b32 s58, v255, 32
	v_readlane_b32 s59, v255, 33
	s_add_u32 s92, s58, 0x2000
	s_addc_u32 s93, s59, 0
	s_add_u32 s0, s58, 0x3000
	s_addc_u32 s1, s59, 0
	v_writelane_b32 v254, s0, 37
	v_readlane_b32 s53, v255, 27
	v_readlane_b32 s54, v255, 28
	v_writelane_b32 v254, s1, 38
	s_add_u32 s0, s58, 0x2200
	s_addc_u32 s1, s59, 0
	v_writelane_b32 v254, s0, 58
	v_readlane_b32 s55, v255, 29
	v_readlane_b32 s56, v255, 30
	v_writelane_b32 v254, s1, 59
	s_add_u32 s0, s58, 0x3200
	s_addc_u32 s1, s59, 0
	v_readlane_b32 s57, v255, 31
	v_readlane_b32 s60, v255, 34
	v_readlane_b32 s61, v255, 35
	v_readlane_b32 s62, v255, 36
	v_readlane_b32 s63, v255, 37
	v_readlane_b32 s64, v255, 38
	v_readlane_b32 s65, v255, 39
	v_readlane_b32 s66, v255, 40
	v_readlane_b32 s67, v255, 41
	v_writelane_b32 v255, s0, 20
	s_mov_b32 s11, 0
	v_mov_b32_e32 v28, 0
	v_writelane_b32 v255, s1, 21
	s_add_u32 s0, s58, 0x2400
	s_addc_u32 s1, s59, 0
	v_writelane_b32 v255, s0, 22
	s_movk_i32 s3, 0x1e20
	s_movk_i32 s94, 0x1000
	v_writelane_b32 v255, s1, 23
	s_add_u32 s0, s58, 0x3400
	s_addc_u32 s1, s59, 0
	v_writelane_b32 v255, s0, 24
	s_mov_b32 s95, 0xbfb8aa3b
	s_mov_b32 s52, 0x800000
	v_writelane_b32 v255, s1, 25
	s_add_u32 s0, s58, 0x2600
	s_addc_u32 s1, s59, 0
	v_writelane_b32 v254, s0, 60
	s_mov_b32 s53, 0x3f317217
	s_mov_b32 s54, 0x7f800000
	v_writelane_b32 v254, s1, 61
	s_add_u32 s0, s58, 0x3600
	s_addc_u32 s1, s59, 0
	v_writelane_b32 v255, s0, 0
	s_mov_b32 s4, 0x3e3504f3
	s_movk_i32 s55, 0x800
	v_writelane_b32 v255, s1, 1
	s_add_u32 s0, s58, 0x2800
	s_addc_u32 s1, s59, 0
	v_writelane_b32 v255, s0, 2
	v_mov_b32_e32 v73, 0x42800000
	v_mov_b32_e32 v74, 0x1800
	v_writelane_b32 v255, s1, 3
	s_add_u32 s0, s58, 0x3800
	s_addc_u32 s1, s59, 0
	v_writelane_b32 v255, s0, 4
	v_mov_b32_e32 v75, 0x1600
	v_mov_b32_e32 v76, 0x3e000000
	v_writelane_b32 v255, s1, 5
	s_add_u32 s0, s58, 0x2a00
	s_addc_u32 s1, s59, 0
	v_writelane_b32 v255, s0, 6
	v_mov_b32_e32 v77, 0x41b17218
	v_mov_b32_e32 v78, 0xc00
	v_writelane_b32 v255, s1, 7
	s_add_u32 s0, s58, 0x3a00
	s_addc_u32 s1, s59, 0
	v_writelane_b32 v255, s0, 8
	v_mov_b32_e32 v79, 0xb00
	v_mov_b32_e32 v80, 0x1000
	v_writelane_b32 v255, s1, 9
	s_add_u32 s0, s58, 0x2c00
	s_addc_u32 s1, s59, 0
	v_writelane_b32 v255, s0, 10
	s_waitcnt lgkmcnt(0)
	s_barrier
	v_writelane_b32 v255, s1, 11
	s_add_u32 s0, s58, 0x3c00
	s_addc_u32 s1, s59, 0
	s_add_u32 s96, s58, 0x2e00
	s_addc_u32 s97, s59, 0
	s_add_u32 s90, s58, 0x3e00
	v_writelane_b32 v255, s0, 12
	s_addc_u32 s91, s59, 0
	s_add_i32 s5, 0, 0x10010
	v_writelane_b32 v255, s1, 13
	v_mov_b32_e32 v72, s5
	s_mov_b32 s99, -1
	s_mov_b32 s100, 0
	s_cmp_lg_u32 s28, 0x200
	s_cbranch_scc1 .Lmap_done_1
	s_movk_i32 s100, 0x140
	s_cmp_ge_u32 s2, 0x100
	s_cbranch_scc1 .Lmap_hi_1
	s_mov_b32 s99, s2
	s_cmp_lt_u32 s2, 160
	s_cbranch_scc1 .Lmap_done_1
	s_add_u32 s99, s2, 0x60
	s_cmp_lt_u32 s2, 192
	s_cbranch_scc1 .Lmap_done_1
	s_sub_u32 s99, s2, 32
	s_cmp_lt_u32 s2, 224
	s_cbranch_scc1 .Lmap_done_1
	s_add_u32 s99, s2, 64
	s_branch .Lmap_done_1

.Lq_dyn_1:
	v_mov_b32_e32 v1, 1
	global_atomic_add v1, v28, v1, s[48:49] offset:4 sc0
	s_waitcnt vmcnt(0)
	v_add_u32_e32 v0, s100, v1
.Lq_wr_1:
	v_mov_b32_e32 v1, s5
	s_nop 0
	ds_write_b32 v1, v0

	.amdhsa_kernel _Z6k_mega6Params
		.amdhsa_group_segment_fixed_size 0
		.amdhsa_private_segment_fixed_size 0
		.amdhsa_kernarg_size 584
		.amdhsa_user_sgpr_count 2
		.amdhsa_user_sgpr_dispatch_ptr 0
		.amdhsa_user_sgpr_queue_ptr 0
		.amdhsa_user_sgpr_kernarg_segment_ptr 1
		.amdhsa_user_sgpr_dispatch_id 0
		.amdhsa_user_sgpr_kernarg_preload_length 0
		.amdhsa_user_sgpr_kernarg_preload_offset 0
		.amdhsa_user_sgpr_private_segment_size 0
		.amdhsa_uses_dynamic_stack 0
		.amdhsa_enable_private_segment 0
		.amdhsa_system_sgpr_workgroup_id_x 1
		.amdhsa_system_sgpr_workgroup_id_y 0
		.amdhsa_system_sgpr_workgroup_id_z 0
		.amdhsa_system_sgpr_workgroup_info 0
		.amdhsa_system_vgpr_workitem_id 2
		.amdhsa_next_free_vgpr 256
		.amdhsa_next_free_sgpr 102
		.amdhsa_accum_offset 256
		.amdhsa_reserve_vcc 1
		.amdhsa_float_round_mode_32 0
		.amdhsa_float_round_mode_16_64 0
		.amdhsa_float_denorm_mode_32 3
		.amdhsa_float_denorm_mode_16_64 3
		.amdhsa_dx10_clamp 1
		.amdhsa_ieee_mode 1
		.amdhsa_fp16_overflow 0
		.amdhsa_tg_split 0
		.amdhsa_exception_fp_ieee_invalid_op 0
		.amdhsa_exception_fp_denorm_src 0
		.amdhsa_exception_fp_ieee_div_zero 0
		.amdhsa_exception_fp_ieee_overflow 0
		.amdhsa_exception_fp_ieee_underflow 0
		.amdhsa_exception_fp_ieee_inexact 0
		.amdhsa_exception_int_div_zero 0
	.end_amdhsa_kernel

amdhsa.kernels:
  - .agpr_count:     0
    .args:
      - .offset:         0
        .size:           328
        .value_kind:     by_value
      - .offset:         328
        .size:           4
        .value_kind:     hidden_block_count_x
      - .offset:         332
        .size:           4
        .value_kind:     hidden_block_count_y
      - .offset:         336
        .size:           4
        .value_kind:     hidden_block_count_z
      - .offset:         340
        .size:           2
        .value_kind:     hidden_group_size_x
      - .offset:         342
        .size:           2
        .value_kind:     hidden_group_size_y
      - .offset:         344
        .size:           2
        .value_kind:     hidden_group_size_z
      - .offset:         346
        .size:           2
        .value_kind:     hidden_remainder_x
      - .offset:         348
        .size:           2
        .value_kind:     hidden_remainder_y
      - .offset:         350
        .size:           2
        .value_kind:     hidden_remainder_z
      - .offset:         368
        .size:           8
        .value_kind:     hidden_global_offset_x
      - .offset:         376
        .size:           8
        .value_kind:     hidden_global_offset_y
      - .offset:         384
        .size:           8
        .value_kind:     hidden_global_offset_z
      - .offset:         392
        .size:           2
        .value_kind:     hidden_grid_dims
      - .offset:         416
        .size:           8
        .value_kind:     hidden_multigrid_sync_arg
      - .offset:         448
        .size:           4
        .value_kind:     hidden_dynamic_lds_size
    .group_segment_fixed_size: 0
    .kernarg_segment_align: 8
    .kernarg_segment_size: 584
    .language:       OpenCL C
    .language_version:
      - 2
      - 0
    .max_flat_workgroup_size: 256
    .name:           _Z6k_mega6Params
    .private_segment_fixed_size: 0
    .sgpr_count:     108
    .sgpr_spill_count: 137
    .symbol:         _Z6k_mega6Params.kd
    .uniform_work_group_size: 1
    .uses_dynamic_stack: false
    .vgpr_count:     256
    .vgpr_spill_count: 0
    .wavefront_size: 64
